# fsdone hand-off polls with a longer sleep (8)
# speedup vs baseline: 1.0079x; 1.0006x over previous
.LBB0_722:
	global_load_dword v0, v161, s[6:7] sc1
	s_waitcnt vmcnt(0)
	v_readfirstlane_b32 s16, v0
	s_cmp_gt_u32 s16, 63
	s_mov_b64 s[16:17], -1
	s_cbranch_scc1 .LBB0_721
	s_sleep 8
	global_load_dword v0, v161, s[6:7] sc1
	s_waitcnt vmcnt(0)
	v_readfirstlane_b32 s16, v0
	s_cmp_lt_u32 s16, 64
	s_mov_b64 s[16:17], -1
	s_cbranch_scc0 .LBB0_721
	s_sleep 8
	global_load_dword v0, v161, s[6:7] sc1
	s_waitcnt vmcnt(0)
	v_readfirstlane_b32 s16, v0
	s_cmp_lt_u32 s16, 64
	s_mov_b64 s[16:17], -1
	s_cbranch_scc0 .LBB0_721
	s_sleep 8
	global_load_dword v0, v161, s[6:7] sc1
	s_waitcnt vmcnt(0)
	v_readfirstlane_b32 s16, v0
	s_cmp_lt_u32 s16, 64
	s_mov_b64 s[16:17], -1
	s_cbranch_scc0 .LBB0_721
	s_sleep 8
	global_load_dword v0, v161, s[6:7] sc1
	s_waitcnt vmcnt(0)
	v_readfirstlane_b32 s16, v0
	s_cmp_lt_u32 s16, 64
	s_mov_b64 s[16:17], -1
	s_cbranch_scc0 .LBB0_721
	s_sleep 8
	global_load_dword v0, v161, s[6:7] sc1
	s_waitcnt vmcnt(0)
	v_readfirstlane_b32 s16, v0
	s_cmp_lt_u32 s16, 64
	s_mov_b64 s[16:17], -1
	s_cbranch_scc0 .LBB0_721
	s_sleep 8
	global_load_dword v0, v161, s[6:7] sc1
	s_waitcnt vmcnt(0)
	v_readfirstlane_b32 s16, v0
	s_cmp_lt_u32 s16, 64
	s_mov_b64 s[16:17], -1
	s_cbranch_scc0 .LBB0_721
	s_sleep 8
	global_load_dword v0, v161, s[6:7] sc1
	s_waitcnt vmcnt(0)
	v_readfirstlane_b32 s16, v0
	s_cmp_lt_u32 s16, 64
	s_mov_b64 s[16:17], -1
	s_cbranch_scc0 .LBB0_721
	s_sleep 8
	global_load_dword v0, v161, s[6:7] sc1
	s_waitcnt vmcnt(0)
	v_readfirstlane_b32 s16, v0
	s_cmp_lt_u32 s16, 64
	s_mov_b64 s[16:17], -1
	s_cbranch_scc0 .LBB0_721
	s_sleep 8
	global_load_dword v0, v161, s[6:7] sc1
	s_waitcnt vmcnt(0)
	v_readfirstlane_b32 s16, v0
	s_cmp_lt_u32 s16, 64
	s_mov_b64 s[16:17], -1
	s_cbranch_scc0 .LBB0_721
	s_sleep 8
	global_load_dword v0, v161, s[6:7] sc1
	s_waitcnt vmcnt(0)
	v_readfirstlane_b32 s16, v0
	s_cmp_lt_u32 s16, 64
	s_mov_b64 s[16:17], -1
	s_cbranch_scc0 .LBB0_721
	s_sleep 8
	global_load_dword v0, v161, s[6:7] sc1
	s_waitcnt vmcnt(0)
	v_readfirstlane_b32 s16, v0
	s_cmp_lt_u32 s16, 64
	s_mov_b64 s[16:17], -1
	s_cbranch_scc0 .LBB0_721
	s_sleep 8
	global_load_dword v0, v161, s[6:7] sc1
	s_waitcnt vmcnt(0)
	v_readfirstlane_b32 s16, v0
	s_cmp_lt_u32 s16, 64
	s_mov_b64 s[16:17], -1
	s_cbranch_scc0 .LBB0_721
	s_add_i32 s19, s19, -13
	s_cmp_eq_u32 s19, 0
	s_cselect_b64 s[16:17], -1, 0
	s_sleep 8
	s_branch .LBB0_721
